# non-temporal stores for the final f32 output rows and the phase-7 residual-stream rows
# speedup vs baseline: 1.0159x; 1.0021x over previous
.LBB0_764:
	v_lshl_add_u64 v[74:75], s[8:9], 0, v[32:33]
	v_lshl_add_u64 v[72:73], s[10:11], 0, v[32:33]
	v_add_co_u32_e64 v104, s[4:5], s23, v74
	v_lshl_add_u64 v[16:17], s[18:19], 0, v[66:67]
	v_lshl_add_u64 v[76:77], s[14:15], 0, v[66:67]
	v_add_co_u32_e32 v102, vcc, 0x4000000, v72
	v_addc_co_u32_e64 v105, s[4:5], 0, v75, s[4:5]
	global_load_dwordx4 v[86:89], v[16:17], off nt
	global_load_dwordx4 v[90:93], v[16:17], off offset:1024 nt
	global_load_dwordx4 v[94:97], v[16:17], off offset:2048 nt
	global_load_dwordx4 v[98:101], v[16:17], off offset:3072 nt
	global_load_dwordx4 v[28:31], v[76:77], off nt
	global_load_dwordx4 v[24:27], v[76:77], off offset:1024 nt
	global_load_dwordx4 v[20:23], v[76:77], off offset:2048 nt
	s_nop 0
	global_load_dwordx4 v[16:19], v[76:77], off offset:3072 nt
	v_add_co_u32_e64 v76, s[4:5], s25, v72
	v_addc_co_u32_e32 v103, vcc, 0, v73, vcc
	s_nop 0
	v_addc_co_u32_e64 v77, s[4:5], 0, v73, s[4:5]
	global_load_dwordx2 v[106:107], v[104:105], off offset:1536 nt
	global_load_dwordx2 v[108:109], v[104:105], off nt
	global_load_dwordx2 v[110:111], v[104:105], off offset:512 nt
	global_load_dwordx2 v[112:113], v[104:105], off offset:1024 nt
	global_load_dwordx2 v[72:73], v[102:103], off offset:1536 nt
	s_nop 0
	global_load_dwordx2 v[104:105], v[102:103], off nt
	global_load_dwordx2 v[114:115], v[102:103], off offset:512 nt
	global_load_dwordx2 v[116:117], v[102:103], off offset:1024 nt
	v_lshl_add_u64 v[70:71], s[16:17], 0, v[32:33]
	v_add_co_u32_e64 v74, s[4:5], s25, v74
	v_lshl_add_u64 v[78:79], s[12:13], 0, v[32:33]
	s_nop 0
	v_addc_co_u32_e64 v75, s[4:5], 0, v75, s[4:5]
	s_add_i32 s22, s22, 2
	s_add_u32 s8, s8, 0x1000
	s_addc_u32 s9, s9, 0
	s_add_u32 s10, s10, 0x1000
	s_addc_u32 s11, s11, 0
	s_add_u32 s12, s12, 0x1000
	s_addc_u32 s13, s13, 0
	s_add_u32 s14, s14, 0x2000
	s_addc_u32 s15, s15, 0
	s_add_u32 s16, s16, 0x1000
	s_addc_u32 s17, s17, 0
	s_add_u32 s18, s18, 0x2000
	s_addc_u32 s19, s19, 0
	s_cmp_lt_i32 s22, s21
	s_waitcnt vmcnt(7)
	v_lshlrev_b32_e32 v103, 16, v106
	s_waitcnt vmcnt(6)
	v_lshlrev_b32_e32 v120, 16, v108
	v_and_b32_e32 v121, 0xffff0000, v108
	v_lshlrev_b32_e32 v108, 16, v109
	v_and_b32_e32 v109, 0xffff0000, v109
	s_waitcnt vmcnt(5)
	v_lshlrev_b32_e32 v123, 16, v111
	v_lshlrev_b32_e32 v122, 16, v110
	v_and_b32_e32 v111, 0xffff0000, v111
	v_and_b32_e32 v110, 0xffff0000, v110
	s_waitcnt vmcnt(2)
	v_lshlrev_b32_e32 v130, 16, v104
	v_and_b32_e32 v131, 0xffff0000, v104
	v_lshlrev_b32_e32 v104, 16, v105
	v_and_b32_e32 v105, 0xffff0000, v105
	s_waitcnt vmcnt(1)
	v_lshlrev_b32_e32 v133, 16, v115
	v_lshlrev_b32_e32 v132, 16, v114
	v_and_b32_e32 v115, 0xffff0000, v115
	v_and_b32_e32 v114, 0xffff0000, v114
	v_lshlrev_b32_e32 v124, 16, v112
	v_and_b32_e32 v125, 0xffff0000, v112
	v_lshlrev_b32_e32 v112, 16, v113
	v_and_b32_e32 v113, 0xffff0000, v113
	v_lshlrev_b32_e32 v127, 16, v72
	v_mul_f32_e32 v102, v109, v109
	v_pk_mul_f32 v[136:137], v[110:111], v[110:111]
	v_mul_f32_e32 v126, v121, v121
	v_mul_f32_e32 v144, v105, v105
	v_pk_mul_f32 v[146:147], v[114:115], v[114:115]
	v_mul_f32_e32 v148, v131, v131
	v_and_b32_e32 v119, 0xffff0000, v106
	v_lshlrev_b32_e32 v106, 16, v107
	s_waitcnt vmcnt(0)
	v_lshlrev_b32_e32 v134, 16, v116
	v_and_b32_e32 v135, 0xffff0000, v116
	v_lshlrev_b32_e32 v116, 16, v117
	v_and_b32_e32 v117, 0xffff0000, v117
	v_mov_b32_e32 v139, v103
	v_mul_f32_e32 v138, v125, v125
	v_mul_f32_e32 v140, v113, v113
	v_mov_b32_e32 v142, v122
	v_mov_b32_e32 v143, v110
	v_mov_b32_e32 v110, v123
	v_mov_b32_e32 v141, v127
	v_mov_b32_e32 v154, v132
	v_mov_b32_e32 v155, v114
	v_mov_b32_e32 v114, v133
	v_pk_fma_f32 v[156:157], v[108:109], v[108:109], v[102:103] op_sel_hi:[1,1,0]
	v_pk_fma_f32 v[122:123], v[122:123], v[122:123], v[136:137]
	v_pk_fma_f32 v[136:137], v[120:121], v[120:121], v[126:127] op_sel_hi:[1,1,0]
	v_pk_fma_f32 v[144:145], v[104:105], v[104:105], v[144:145] op_sel_hi:[1,1,0]
	v_pk_fma_f32 v[132:133], v[132:133], v[132:133], v[146:147]
	v_pk_fma_f32 v[146:147], v[130:131], v[130:131], v[148:149] op_sel_hi:[1,1,0]
	v_and_b32_e32 v129, 0xffff0000, v72
	v_lshlrev_b32_e32 v72, 16, v73
	v_and_b32_e32 v73, 0xffff0000, v73
	v_mul_f32_e32 v153, v106, v106
	v_mul_f32_e32 v150, v135, v135
	v_mul_f32_e32 v152, v117, v117
	v_pk_fma_f32 v[158:159], v[124:125], v[124:125], v[138:139] op_sel_hi:[1,1,0]
	v_pk_fma_f32 v[160:161], v[112:113], v[112:113], v[140:141] op_sel_hi:[1,1,0]
	v_mov_b32_e32 v102, v136
	v_mov_b32_e32 v138, v156
	v_mov_b32_e32 v126, v146
	v_mov_b32_e32 v140, v144
	v_and_b32_e32 v107, 0xffff0000, v107
	v_mul_f32_e32 v85, v119, v119
	v_mov_b32_e32 v118, v103
	v_mul_f32_e32 v163, v129, v129
	v_mul_f32_e32 v164, v72, v72
	v_mul_f32_e32 v165, v73, v73
	v_mov_b32_e32 v128, v127
	v_pk_fma_f32 v[148:149], v[134:135], v[134:135], v[150:151] op_sel_hi:[1,1,0]
	v_pk_fma_f32 v[150:151], v[116:117], v[116:117], v[152:153] op_sel_hi:[1,1,0]
	v_pk_add_f32 v[136:137], v[136:137], v[156:157]
	v_pk_add_f32 v[122:123], v[122:123], v[122:123] op_sel:[0,1] op_sel_hi:[1,0]
	v_pk_add_f32 v[144:145], v[146:147], v[144:145]
	v_pk_add_f32 v[132:133], v[132:133], v[132:133] op_sel:[0,1] op_sel_hi:[1,0]
	v_pk_mul_f32 v[102:103], v[102:103], v[138:139]
	v_pk_mul_f32 v[126:127], v[126:127], v[140:141]
	v_mul_f32_e32 v162, v107, v107
	v_mov_b32_e32 v149, v164
	v_mov_b32_e32 v151, v165
	v_mov_b32_e32 v123, v85
	v_mov_b32_e32 v133, v163
	v_mov_b32_e32 v137, v103
	v_mov_b32_e32 v145, v127
	v_mov_b32_e32 v159, v153
	v_mov_b32_e32 v161, v162
	v_pk_add_f32 v[140:141], v[148:149], v[150:151]
	v_pk_add_f32 v[102:103], v[136:137], v[122:123]
	v_pk_add_f32 v[122:123], v[144:145], v[132:133]
	v_pk_add_f32 v[138:139], v[158:159], v[160:161]
	v_pk_add_f32 v[122:123], v[122:123], v[140:141]
	v_pk_add_f32 v[102:103], v[102:103], v[138:139]
	v_add_f32_e32 v85, v122, v123
	v_mov_b32_e32 v126, v102
	ds_bpermute_b32 v102, v69, v85
	s_waitcnt lgkmcnt(0)
	v_add_f32_e32 v85, v85, v102
	ds_bpermute_b32 v102, v80, v85
	s_waitcnt lgkmcnt(0)
	v_add_f32_e32 v85, v85, v102
	ds_bpermute_b32 v102, v81, v85
	s_waitcnt lgkmcnt(0)
	v_add_f32_e32 v85, v85, v102
	ds_bpermute_b32 v102, v82, v85
	s_waitcnt lgkmcnt(0)
	v_add_f32_e32 v85, v85, v102
	ds_bpermute_b32 v102, v83, v85
	s_waitcnt lgkmcnt(0)
	v_add_f32_e32 v85, v85, v102
	ds_bpermute_b32 v102, v84, v85
	s_waitcnt lgkmcnt(0)
	v_add_f32_e32 v85, v85, v102
	v_fmamk_f32 v85, v85, 0x3a800000, v68
	v_mul_f32_e32 v102, 0x4b800000, v85
	v_cmp_gt_f32_e32 vcc, s24, v85
	s_nop 1
	v_cndmask_b32_e32 v85, v85, v102, vcc
	v_rsq_f32_e32 v85, v85
	s_nop 0
	v_mul_f32_e32 v102, 0x45800000, v85
	v_cndmask_b32_e32 v102, v85, v102, vcc
	v_pk_mul_f32 v[122:123], v[102:103], v[130:131] op_sel_hi:[0,1]
	v_pk_mul_f32 v[104:105], v[102:103], v[104:105] op_sel_hi:[0,1]
	v_pk_mul_f32 v[130:131], v[102:103], v[154:155] op_sel_hi:[0,1]
	v_pk_mul_f32 v[114:115], v[102:103], v[114:115] op_sel_hi:[0,1]
	v_pk_mul_f32 v[132:133], v[102:103], v[134:135] op_sel_hi:[0,1]
	v_pk_mul_f32 v[116:117], v[102:103], v[116:117] op_sel_hi:[0,1]
	v_pk_mul_f32 v[128:129], v[102:103], v[128:129] op_sel_hi:[0,1]
	v_pk_mul_f32 v[72:73], v[102:103], v[72:73] op_sel_hi:[0,1]
	v_pk_fma_f32 v[88:89], v[34:35], v[104:105], v[88:89]
	v_pk_fma_f32 v[86:87], v[36:37], v[122:123], v[86:87]
	v_pk_fma_f32 v[92:93], v[38:39], v[114:115], v[92:93]
	v_pk_fma_f32 v[90:91], v[40:41], v[130:131], v[90:91]
	v_pk_fma_f32 v[96:97], v[42:43], v[116:117], v[96:97]
	v_pk_fma_f32 v[94:95], v[44:45], v[132:133], v[94:95]
	v_pk_fma_f32 v[72:73], v[46:47], v[72:73], v[100:101]
	v_pk_fma_f32 v[98:99], v[48:49], v[128:129], v[98:99]
	v_cvt_pk_bf16_f32 v86, v86, v87
	v_cvt_pk_bf16_f32 v87, v88, v89
	v_cvt_pk_bf16_f32 v88, v90, v91
	v_cvt_pk_bf16_f32 v89, v92, v93
	v_cvt_pk_bf16_f32 v90, v94, v95
	v_cvt_pk_bf16_f32 v91, v96, v97
	v_cvt_pk_bf16_f32 v92, v98, v99
	v_cvt_pk_bf16_f32 v93, v72, v73
	global_store_dwordx2 v[70:71], v[86:87], off nt
	global_store_dwordx2 v[70:71], v[88:89], off offset:512 nt
	global_store_dwordx2 v[70:71], v[90:91], off offset:1024 nt
	v_lshlrev_b32_e32 v95, 16, v87
	v_lshlrev_b32_e32 v94, 16, v86
	v_and_b32_e32 v87, 0xffff0000, v87
	v_and_b32_e32 v86, 0xffff0000, v86
	v_lshlrev_b32_e32 v97, 16, v89
	v_lshlrev_b32_e32 v96, 16, v88
	v_and_b32_e32 v89, 0xffff0000, v89
	v_and_b32_e32 v88, 0xffff0000, v88
	v_lshlrev_b32_e32 v72, 16, v90
	v_and_b32_e32 v73, 0xffff0000, v90
	global_store_dwordx2 v[70:71], v[92:93], off offset:1536 nt
	v_lshlrev_b32_e32 v70, 16, v92
	v_lshlrev_b32_e32 v90, 16, v91
	v_pk_mul_f32 v[98:99], v[86:87], v[86:87]
	v_pk_mul_f32 v[100:101], v[88:89], v[88:89]
	v_and_b32_e32 v91, 0xffff0000, v91
	v_mul_f32_e32 v71, v72, v72
	v_mul_f32_e32 v105, v73, v73
	v_mul_f32_e32 v102, v90, v90
	v_mov_b32_e32 v104, v70
	v_mov_b32_e32 v116, v94
	v_mov_b32_e32 v117, v86
	v_mov_b32_e32 v86, v95
	v_mov_b32_e32 v122, v96
	v_mov_b32_e32 v123, v88
	v_mov_b32_e32 v88, v97
	v_pk_fma_f32 v[94:95], v[94:95], v[94:95], v[98:99]
	v_pk_fma_f32 v[96:97], v[96:97], v[96:97], v[100:101]
	v_and_b32_e32 v85, 0xffff0000, v92
	v_lshlrev_b32_e32 v92, 16, v93
	v_and_b32_e32 v93, 0xffff0000, v93
	v_pk_fma_f32 v[98:99], v[90:91], v[90:91], v[102:103] op_sel_hi:[1,1,0]
	v_pk_add_f32 v[100:101], v[70:71], v[104:105]
	v_pk_add_f32 v[94:95], v[94:95], v[94:95] op_sel_hi:[0,1]
	v_pk_add_f32 v[96:97], v[96:97], v[96:97] op_sel_hi:[0,1]
	v_mul_f32_e32 v114, v70, v70
	v_mul_f32_e32 v98, v85, v85
	v_mov_b32_e32 v115, v101
	v_mul_f32_e32 v94, v92, v92
	v_mul_f32_e32 v96, v93, v93
	v_pk_add_f32 v[98:99], v[114:115], v[98:99]
	v_pk_add_f32 v[94:95], v[94:95], v[96:97]
	v_mov_b32_e32 v71, v85
	v_pk_add_f32 v[94:95], v[98:99], v[94:95]
	s_nop 0
	v_mov_b32_e32 v127, v94
	v_mov_b32_e32 v94, v103
	v_pk_add_f32 v[94:95], v[126:127], v[94:95]
	ds_bpermute_b32 v97, v69, v95
	ds_bpermute_b32 v96, v69, v94
	s_waitcnt lgkmcnt(0)
	v_pk_add_f32 v[94:95], v[94:95], v[96:97]
	ds_bpermute_b32 v97, v80, v95
	ds_bpermute_b32 v96, v80, v94
	s_waitcnt lgkmcnt(0)
	v_pk_add_f32 v[94:95], v[94:95], v[96:97]
	ds_bpermute_b32 v97, v81, v95
	ds_bpermute_b32 v96, v81, v94
	s_waitcnt lgkmcnt(0)
	v_pk_add_f32 v[94:95], v[94:95], v[96:97]
	ds_bpermute_b32 v97, v82, v95
	ds_bpermute_b32 v96, v82, v94
	s_waitcnt lgkmcnt(0)
	v_pk_add_f32 v[94:95], v[94:95], v[96:97]
	ds_bpermute_b32 v97, v83, v95
	ds_bpermute_b32 v96, v83, v94
	s_waitcnt lgkmcnt(0)
	v_pk_add_f32 v[94:95], v[94:95], v[96:97]
	ds_bpermute_b32 v97, v84, v95
	ds_bpermute_b32 v96, v84, v94
	s_waitcnt lgkmcnt(0)
	v_pk_add_f32 v[94:95], v[94:95], v[96:97]
	s_nop 0
	v_pk_fma_f32 v[94:95], v[94:95], s[20:21], v[68:69] op_sel_hi:[1,0,0]
	s_nop 0
	v_mul_f32_e32 v85, 0x4b800000, v95
	v_mul_f32_e32 v96, 0x4b800000, v94
	v_cmp_gt_f32_e32 vcc, s24, v94
	v_cmp_gt_f32_e64 s[4:5], s24, v95
	s_nop 0
	v_cndmask_b32_e32 v94, v94, v96, vcc
	v_cndmask_b32_e64 v85, v95, v85, s[4:5]
	v_rsq_f32_e32 v85, v85
	v_rsq_f32_e32 v95, v94
	v_mul_f32_e32 v94, 0x45800000, v85
	v_mul_f32_e32 v96, 0x45800000, v95
	v_cndmask_b32_e64 v94, v85, v94, s[4:5]
	v_cndmask_b32_e32 v96, v95, v96, vcc
	v_pk_mul_f32 v[98:99], v[94:95], v[116:117] op_sel_hi:[0,1]
	v_pk_mul_f32 v[86:87], v[94:95], v[86:87] op_sel_hi:[0,1]
	v_pk_mul_f32 v[100:101], v[94:95], v[122:123] op_sel_hi:[0,1]
	v_pk_mul_f32 v[88:89], v[94:95], v[88:89] op_sel_hi:[0,1]
	v_pk_mul_f32 v[72:73], v[94:95], v[72:73] op_sel_hi:[0,1]
	v_pk_mul_f32 v[90:91], v[94:95], v[90:91] op_sel_hi:[0,1]
	v_pk_mul_f32 v[70:71], v[94:95], v[70:71] op_sel_hi:[0,1]
	v_pk_mul_f32 v[92:93], v[94:95], v[92:93] op_sel_hi:[0,1]
	v_pk_mul_f32 v[94:95], v[96:97], v[120:121] op_sel_hi:[0,1]
	v_pk_mul_f32 v[102:103], v[96:97], v[108:109] op_sel_hi:[0,1]
	v_pk_mul_f32 v[104:105], v[96:97], v[142:143] op_sel_hi:[0,1]
	v_pk_mul_f32 v[108:109], v[96:97], v[110:111] op_sel_hi:[0,1]
	v_pk_mul_f32 v[110:111], v[96:97], v[124:125] op_sel_hi:[0,1]
	v_pk_mul_f32 v[112:113], v[96:97], v[112:113] op_sel_hi:[0,1]
	v_pk_mul_f32 v[114:115], v[96:97], v[118:119] op_sel_hi:[0,1]
	v_pk_fma_f32 v[86:87], v[50:51], v[86:87], v[2:3]
	v_pk_fma_f32 v[98:99], v[52:53], v[98:99], v[0:1]
	v_pk_fma_f32 v[30:31], v[34:35], v[102:103], v[30:31]
	v_pk_fma_f32 v[28:29], v[36:37], v[94:95], v[28:29]
	v_pk_fma_f32 v[26:27], v[38:39], v[108:109], v[26:27]
	v_pk_fma_f32 v[24:25], v[40:41], v[104:105], v[24:25]
	v_pk_mul_f32 v[96:97], v[96:97], v[106:107] op_sel_hi:[0,1]
	v_pk_fma_f32 v[88:89], v[54:55], v[88:89], v[6:7]
	v_pk_fma_f32 v[100:101], v[56:57], v[100:101], v[4:5]
	v_pk_fma_f32 v[90:91], v[58:59], v[90:91], v[10:11]
	v_pk_fma_f32 v[72:73], v[60:61], v[72:73], v[8:9]
	v_pk_fma_f32 v[92:93], v[62:63], v[92:93], v[14:15]
	v_pk_fma_f32 v[70:71], v[64:65], v[70:71], v[12:13]
	v_pk_fma_f32 v[22:23], v[42:43], v[112:113], v[22:23]
	v_pk_fma_f32 v[20:21], v[44:45], v[110:111], v[20:21]
	v_pk_fma_f32 v[16:17], v[48:49], v[114:115], v[16:17]
	v_cvt_pk_bf16_f32 v94, v98, v99
	v_cvt_pk_bf16_f32 v95, v86, v87
	v_cvt_pk_bf16_f32 v28, v28, v29
	v_cvt_pk_bf16_f32 v29, v30, v31
	v_cvt_pk_bf16_f32 v24, v24, v25
	v_cvt_pk_bf16_f32 v25, v26, v27
	v_pk_fma_f32 v[18:19], v[46:47], v[96:97], v[18:19]
	v_cvt_pk_bf16_f32 v86, v100, v101
	v_cvt_pk_bf16_f32 v87, v88, v89
	v_cvt_pk_bf16_f32 v72, v72, v73
	v_cvt_pk_bf16_f32 v73, v90, v91
	v_cvt_pk_bf16_f32 v70, v70, v71
	v_cvt_pk_bf16_f32 v71, v92, v93
	v_cvt_pk_bf16_f32 v20, v20, v21
	v_cvt_pk_bf16_f32 v21, v22, v23
	v_cvt_pk_bf16_f32 v16, v16, v17
	global_store_dwordx2 v[76:77], v[94:95], off
	global_store_dwordx2 v[76:77], v[86:87], off offset:512
	global_store_dwordx2 v[76:77], v[72:73], off offset:1024
	global_store_dwordx2 v[76:77], v[70:71], off offset:1536
	global_store_dwordx2 v[78:79], v[28:29], off nt
	global_store_dwordx2 v[78:79], v[24:25], off offset:512 nt
	global_store_dwordx2 v[78:79], v[20:21], off offset:1024 nt
	v_lshlrev_b32_e32 v23, 16, v29
	v_lshlrev_b32_e32 v22, 16, v28
	v_and_b32_e32 v27, 0xffff0000, v29
	v_and_b32_e32 v26, 0xffff0000, v28
	v_lshlrev_b32_e32 v29, 16, v25
	v_lshlrev_b32_e32 v28, 16, v24
	v_and_b32_e32 v25, 0xffff0000, v25
	v_and_b32_e32 v24, 0xffff0000, v24
	v_cvt_pk_bf16_f32 v17, v18, v19
	v_lshlrev_b32_e32 v18, 16, v20
	v_and_b32_e32 v19, 0xffff0000, v20
	v_lshlrev_b32_e32 v20, 16, v16
	v_lshlrev_b32_e32 v30, 16, v21
	v_pk_mul_f32 v[70:71], v[26:27], v[26:27]
	v_pk_mul_f32 v[72:73], v[24:25], v[24:25]
	global_store_dwordx2 v[78:79], v[16:17], off offset:1536 nt
	v_and_b32_e32 v79, 0xffff0000, v16
	v_and_b32_e32 v31, 0xffff0000, v21
	v_mul_f32_e32 v21, v18, v18
	v_mul_f32_e32 v77, v19, v19
	v_mul_f32_e32 v78, v30, v30
	v_mov_b32_e32 v76, v20
	v_mov_b32_e32 v88, v22
	v_mov_b32_e32 v89, v26
	v_mov_b32_e32 v26, v23
	v_mov_b32_e32 v90, v28
	v_mov_b32_e32 v91, v24
	v_mov_b32_e32 v24, v29
	v_pk_fma_f32 v[22:23], v[22:23], v[22:23], v[70:71]
	v_pk_fma_f32 v[28:29], v[28:29], v[28:29], v[72:73]
	v_lshlrev_b32_e32 v16, 16, v17
	v_and_b32_e32 v17, 0xffff0000, v17
	v_pk_fma_f32 v[70:71], v[30:31], v[30:31], v[78:79] op_sel_hi:[1,1,0]
	v_pk_add_f32 v[72:73], v[20:21], v[76:77]
	v_pk_add_f32 v[22:23], v[22:23], v[22:23] op_sel_hi:[0,1]
	v_pk_add_f32 v[28:29], v[28:29], v[28:29] op_sel_hi:[0,1]
	v_mul_f32_e32 v86, v20, v20
	v_mul_f32_e32 v70, v79, v79
	v_mov_b32_e32 v87, v73
	v_mul_f32_e32 v22, v16, v16
	v_mul_f32_e32 v28, v17, v17
	v_pk_add_f32 v[70:71], v[86:87], v[70:71]
	v_pk_add_f32 v[22:23], v[22:23], v[28:29]
	v_mov_b32_e32 v21, v79
	v_pk_add_f32 v[22:23], v[70:71], v[22:23]
	s_nop 0
	v_add_f32_e32 v22, v22, v23
	ds_bpermute_b32 v23, v69, v22
	s_waitcnt lgkmcnt(0)
	v_add_f32_e32 v22, v22, v23
	ds_bpermute_b32 v23, v80, v22
	s_waitcnt lgkmcnt(0)
	v_add_f32_e32 v22, v22, v23
	ds_bpermute_b32 v23, v81, v22
	s_waitcnt lgkmcnt(0)
	v_add_f32_e32 v22, v22, v23
	ds_bpermute_b32 v23, v82, v22
	s_waitcnt lgkmcnt(0)
	v_add_f32_e32 v22, v22, v23
	ds_bpermute_b32 v23, v83, v22
	s_waitcnt lgkmcnt(0)
	v_add_f32_e32 v22, v22, v23
	ds_bpermute_b32 v23, v84, v22
	s_waitcnt lgkmcnt(0)
	v_add_f32_e32 v22, v22, v23
	v_fmamk_f32 v22, v22, 0x3a800000, v68
	v_mul_f32_e32 v23, 0x4b800000, v22
	v_cmp_gt_f32_e32 vcc, s24, v22
	s_nop 1
	v_cndmask_b32_e32 v22, v22, v23, vcc
	v_rsq_f32_e32 v22, v22
	s_nop 0
	v_mul_f32_e32 v23, 0x45800000, v22
	v_cndmask_b32_e32 v22, v22, v23, vcc
	v_pk_mul_f32 v[28:29], v[22:23], v[88:89] op_sel_hi:[0,1]
	v_pk_mul_f32 v[26:27], v[22:23], v[26:27] op_sel_hi:[0,1]
	v_pk_mul_f32 v[70:71], v[22:23], v[90:91] op_sel_hi:[0,1]
	v_pk_mul_f32 v[24:25], v[22:23], v[24:25] op_sel_hi:[0,1]
	v_pk_mul_f32 v[18:19], v[22:23], v[18:19] op_sel_hi:[0,1]
	v_pk_mul_f32 v[30:31], v[22:23], v[30:31] op_sel_hi:[0,1]
	v_pk_mul_f32 v[20:21], v[22:23], v[20:21] op_sel_hi:[0,1]
	v_pk_mul_f32 v[16:17], v[22:23], v[16:17] op_sel_hi:[0,1]
	v_pk_fma_f32 v[22:23], v[50:51], v[26:27], v[2:3]
	v_pk_fma_f32 v[26:27], v[52:53], v[28:29], v[0:1]
	v_pk_fma_f32 v[24:25], v[54:55], v[24:25], v[6:7]
	v_pk_fma_f32 v[28:29], v[56:57], v[70:71], v[4:5]
	v_pk_fma_f32 v[30:31], v[58:59], v[30:31], v[10:11]
	v_pk_fma_f32 v[18:19], v[60:61], v[18:19], v[8:9]
	v_pk_fma_f32 v[16:17], v[62:63], v[16:17], v[14:15]
	v_pk_fma_f32 v[20:21], v[64:65], v[20:21], v[12:13]
	v_cvt_pk_bf16_f32 v26, v26, v27
	v_cvt_pk_bf16_f32 v27, v22, v23
	v_cvt_pk_bf16_f32 v22, v28, v29
	v_cvt_pk_bf16_f32 v23, v24, v25
	v_cvt_pk_bf16_f32 v18, v18, v19
	v_cvt_pk_bf16_f32 v19, v30, v31
	v_cvt_pk_bf16_f32 v20, v20, v21
	v_cvt_pk_bf16_f32 v21, v16, v17
	global_store_dwordx2 v[74:75], v[26:27], off
	global_store_dwordx2 v[74:75], v[22:23], off offset:512
	global_store_dwordx2 v[74:75], v[18:19], off offset:1024
	global_store_dwordx2 v[74:75], v[20:21], off offset:1536
	s_cbranch_scc1 .LBB0_764

.LBB0_1714:
	v_add_co_u32_e32 v36, vcc, 0xf8000000, v6
	s_add_i32 s0, s9, s8
	s_nop 0
	v_addc_co_u32_e32 v37, vcc, -1, v7, vcc
	v_add_co_u32_e32 v44, vcc, 0xf8001000, v6
	global_load_dwordx2 v[28:29], v[6:7], off nt
	global_load_dwordx2 v[30:31], v[6:7], off offset:512 nt
	global_load_dwordx2 v[32:33], v[6:7], off offset:1024 nt
	global_load_dwordx2 v[34:35], v[6:7], off offset:1536 nt
	s_ashr_i32 s1, s0, 31
	global_load_dwordx2 v[36:37], v[36:37], off nt
	v_addc_co_u32_e32 v45, vcc, -1, v7, vcc
	s_lshl_b64 s[12:13], s[0:1], 11
	global_load_dwordx2 v[46:47], v[44:45], off offset:-2560 nt
	global_load_dwordx2 v[48:49], v[44:45], off offset:-3584 nt
	global_load_dwordx2 v[50:51], v[44:45], off offset:-3072 nt
	v_lshl_add_u64 v[44:45], v[0:1], 0, s[12:13]
	v_lshl_add_u64 v[52:53], v[2:3], 0, s[12:13]
	global_load_dwordx2 v[54:55], v[44:45], off nt
	global_load_dwordx2 v[56:57], v[44:45], off offset:512 nt
	global_load_dwordx2 v[58:59], v[44:45], off offset:1024 nt
	global_load_dwordx2 v[60:61], v[44:45], off offset:1536 nt
	global_load_dwordx2 v[62:63], v[52:53], off offset:1536 nt
	global_load_dwordx2 v[64:65], v[52:53], off nt
	global_load_dwordx2 v[66:67], v[52:53], off offset:512 nt
	global_load_dwordx2 v[70:71], v[52:53], off offset:1024 nt
	s_lshl_b64 s[0:1], s[0:1], 12
	v_lshl_add_u64 v[68:69], v[4:5], 0, s[0:1]
	s_add_i32 s8, s8, 2
	v_lshl_add_u64 v[6:7], v[6:7], 0, s[4:5]
	s_cmp_lt_i32 s8, s3
	s_waitcnt vmcnt(14)
	v_lshlrev_b32_e32 v72, 16, v31
	v_and_b32_e32 v73, 0xffff0000, v31
	s_waitcnt vmcnt(13)
	v_lshlrev_b32_e32 v76, 16, v33
	v_and_b32_e32 v77, 0xffff0000, v33
	s_waitcnt vmcnt(11)
	v_and_b32_e32 v31, 0xffff0000, v36
	v_and_b32_e32 v33, 0xffff0000, v37
	v_lshlrev_b32_e32 v52, 16, v30
	v_and_b32_e32 v53, 0xffff0000, v30
	v_lshlrev_b32_e32 v74, 16, v32
	v_and_b32_e32 v75, 0xffff0000, v32
	v_lshlrev_b32_e32 v78, 16, v34
	v_and_b32_e32 v79, 0xffff0000, v34
	v_lshlrev_b32_e32 v80, 16, v35
	v_and_b32_e32 v81, 0xffff0000, v35
	v_lshlrev_b32_e32 v30, 16, v36
	v_lshlrev_b32_e32 v32, 16, v37
	s_waitcnt vmcnt(10)
	v_lshlrev_b32_e32 v35, 16, v46
	v_and_b32_e32 v37, 0xffff0000, v46
	v_mul_f32_e32 v34, v33, v33
	s_waitcnt vmcnt(9)
	v_lshlrev_b32_e32 v83, 16, v49
	v_lshlrev_b32_e32 v82, 16, v48
	v_and_b32_e32 v49, 0xffff0000, v49
	v_and_b32_e32 v48, 0xffff0000, v48
	s_waitcnt vmcnt(8)
	v_and_b32_e32 v85, 0xffff0000, v50
	v_mul_f32_e32 v36, v31, v31
	v_lshlrev_b32_e32 v84, 16, v50
	v_lshlrev_b32_e32 v50, 16, v51
	v_and_b32_e32 v51, 0xffff0000, v51
	s_waitcnt vmcnt(5)
	v_lshlrev_b32_e32 v90, 16, v58
	v_and_b32_e32 v91, 0xffff0000, v58
	v_lshlrev_b32_e32 v92, 16, v59
	v_and_b32_e32 v93, 0xffff0000, v59
	s_waitcnt vmcnt(3)
	v_lshlrev_b32_e32 v59, 16, v62
	v_pk_fma_f32 v[98:99], v[32:33], v[32:33], v[34:35] op_sel_hi:[1,1,0]
	v_pk_mul_f32 v[100:101], v[48:49], v[48:49]
	v_pk_fma_f32 v[102:103], v[30:31], v[30:31], v[36:37] op_sel_hi:[1,1,0]
	v_mul_f32_e32 v58, v85, v85
	s_waitcnt vmcnt(2)
	v_lshlrev_b32_e32 v106, 16, v64
	v_and_b32_e32 v107, 0xffff0000, v64
	v_lshlrev_b32_e32 v64, 16, v65
	v_and_b32_e32 v65, 0xffff0000, v65
	s_waitcnt vmcnt(1)
	v_lshlrev_b32_e32 v109, 16, v67
	v_lshlrev_b32_e32 v108, 16, v66
	v_and_b32_e32 v67, 0xffff0000, v67
	v_and_b32_e32 v66, 0xffff0000, v66
	v_lshlrev_b32_e32 v46, 16, v47
	v_and_b32_e32 v47, 0xffff0000, v47
	v_lshlrev_b32_e32 v94, 16, v60
	v_and_b32_e32 v95, 0xffff0000, v60
	v_lshlrev_b32_e32 v96, 16, v61
	v_and_b32_e32 v97, 0xffff0000, v61
	v_and_b32_e32 v61, 0xffff0000, v62
	v_mov_b32_e32 v105, v35
	v_mul_f32_e32 v60, v51, v51
	v_mov_b32_e32 v112, v82
	v_mov_b32_e32 v113, v48
	v_mov_b32_e32 v48, v83
	v_pk_fma_f32 v[82:83], v[82:83], v[82:83], v[100:101]
	v_mov_b32_e32 v34, v102
	v_mov_b32_e32 v104, v98
	v_pk_fma_f32 v[100:101], v[84:85], v[84:85], v[58:59] op_sel_hi:[1,1,0]
	v_mul_f32_e32 v58, v65, v65
	v_pk_mul_f32 v[114:115], v[66:67], v[66:67]
	v_mul_f32_e32 v116, v107, v107
	v_mov_b32_e32 v117, v59
	v_mul_f32_e32 v119, v46, v46
	v_mul_f32_e32 v121, v47, v47
	s_waitcnt vmcnt(0)
	v_lshlrev_b32_e32 v110, 16, v70
	v_and_b32_e32 v111, 0xffff0000, v70
	v_lshlrev_b32_e32 v70, 16, v71
	v_and_b32_e32 v71, 0xffff0000, v71
	v_mov_b32_e32 v36, v35
	v_pk_add_f32 v[98:99], v[102:103], v[98:99]
	v_pk_fma_f32 v[102:103], v[50:51], v[50:51], v[60:61] op_sel_hi:[1,1,0]
	v_mov_b32_e32 v122, v108
	v_mov_b32_e32 v123, v66
	v_mov_b32_e32 v66, v109
	v_pk_mul_f32 v[34:35], v[34:35], v[104:105]
	v_pk_fma_f32 v[104:105], v[64:65], v[64:65], v[58:59] op_sel_hi:[1,1,0]
	v_pk_fma_f32 v[108:109], v[108:109], v[108:109], v[114:115]
	v_pk_fma_f32 v[114:115], v[106:107], v[106:107], v[116:117] op_sel_hi:[1,1,0]
	v_lshlrev_b32_e32 v62, 16, v63
	v_and_b32_e32 v63, 0xffff0000, v63
	v_mul_f32_e32 v118, v111, v111
	v_mul_f32_e32 v120, v71, v71
	v_mov_b32_e32 v101, v119
	v_mov_b32_e32 v103, v121
	v_mov_b32_e32 v58, v114
	v_mov_b32_e32 v116, v104
	v_mul_f32_e32 v43, v37, v37
	v_mul_f32_e32 v124, v61, v61
	v_mul_f32_e32 v125, v62, v62
	v_mul_f32_e32 v126, v63, v63
	v_mov_b32_e32 v60, v59
	v_pk_add_f32 v[82:83], v[82:83], v[82:83] op_sel:[0,1] op_sel_hi:[1,0]
	v_pk_fma_f32 v[118:119], v[110:111], v[110:111], v[118:119] op_sel_hi:[1,1,0]
	v_pk_fma_f32 v[120:121], v[70:71], v[70:71], v[120:121] op_sel_hi:[1,1,0]
	v_mov_b32_e32 v99, v35
	v_pk_add_f32 v[34:35], v[100:101], v[102:103]
	v_pk_add_f32 v[100:101], v[114:115], v[104:105]
	v_pk_add_f32 v[102:103], v[108:109], v[108:109] op_sel:[0,1] op_sel_hi:[1,0]
	v_pk_mul_f32 v[58:59], v[58:59], v[116:117]
	v_mov_b32_e32 v83, v43
	v_mov_b32_e32 v119, v125
	v_mov_b32_e32 v121, v126
	v_mov_b32_e32 v103, v124
	v_mov_b32_e32 v101, v59
	v_pk_add_f32 v[82:83], v[98:99], v[82:83]
	v_pk_add_f32 v[98:99], v[118:119], v[120:121]
	v_pk_add_f32 v[58:59], v[100:101], v[102:103]
	v_pk_add_f32 v[34:35], v[82:83], v[34:35]
	v_pk_add_f32 v[58:59], v[58:59], v[98:99]
	v_mov_b32_e32 v83, v34
	v_mov_b32_e32 v82, v58
	v_mov_b32_e32 v34, v59
	v_pk_add_f32 v[34:35], v[82:83], v[34:35]
	ds_bpermute_b32 v59, v27, v35
	ds_bpermute_b32 v58, v27, v34
	v_lshlrev_b32_e32 v44, 16, v28
	v_and_b32_e32 v45, 0xffff0000, v28
	v_lshlrev_b32_e32 v28, 16, v29
	v_and_b32_e32 v29, 0xffff0000, v29
	s_waitcnt lgkmcnt(0)
	v_pk_add_f32 v[34:35], v[34:35], v[58:59]
	ds_bpermute_b32 v59, v38, v35
	ds_bpermute_b32 v58, v38, v34
	v_lshlrev_b32_e32 v86, 16, v54
	v_and_b32_e32 v87, 0xffff0000, v54
	v_lshlrev_b32_e32 v54, 16, v55
	v_and_b32_e32 v55, 0xffff0000, v55
	s_waitcnt lgkmcnt(0)
	v_pk_add_f32 v[34:35], v[34:35], v[58:59]
	ds_bpermute_b32 v59, v39, v35
	ds_bpermute_b32 v58, v39, v34
	v_lshlrev_b32_e32 v88, 16, v56
	v_and_b32_e32 v89, 0xffff0000, v56
	v_lshlrev_b32_e32 v56, 16, v57
	v_and_b32_e32 v57, 0xffff0000, v57
	s_waitcnt lgkmcnt(0)
	v_pk_add_f32 v[34:35], v[34:35], v[58:59]
	ds_bpermute_b32 v59, v40, v35
	ds_bpermute_b32 v58, v40, v34
	s_waitcnt lgkmcnt(0)
	v_pk_add_f32 v[34:35], v[34:35], v[58:59]
	ds_bpermute_b32 v59, v41, v35
	ds_bpermute_b32 v58, v41, v34
	s_waitcnt lgkmcnt(0)
	v_pk_add_f32 v[34:35], v[34:35], v[58:59]
	ds_bpermute_b32 v59, v42, v35
	ds_bpermute_b32 v58, v42, v34
	s_waitcnt lgkmcnt(0)
	v_pk_add_f32 v[34:35], v[34:35], v[58:59]
	s_nop 0
	v_pk_fma_f32 v[34:35], v[34:35], s[2:3], v[26:27] op_sel_hi:[1,0,0]
	s_nop 0
	v_mul_f32_e32 v43, 0x4b800000, v35
	v_cmp_gt_f32_e64 s[0:1], s10, v35
	v_mul_f32_e32 v58, 0x4b800000, v34
	v_cmp_gt_f32_e32 vcc, s10, v34
	v_cndmask_b32_e64 v35, v35, v43, s[0:1]
	v_rsq_f32_e32 v35, v35
	v_cndmask_b32_e32 v34, v34, v58, vcc
	v_rsq_f32_e32 v43, v34
	v_mul_f32_e32 v34, 0x45800000, v35
	v_cndmask_b32_e64 v34, v35, v34, s[0:1]
	v_mul_f32_e32 v58, 0x45800000, v43
	v_cndmask_b32_e32 v58, v43, v58, vcc
	v_pk_mul_f32 v[82:83], v[34:35], v[30:31] op_sel_hi:[0,1]
	v_pk_mul_f32 v[30:31], v[34:35], v[32:33] op_sel_hi:[0,1]
	v_pk_mul_f32 v[32:33], v[34:35], v[112:113] op_sel_hi:[0,1]
	v_pk_mul_f32 v[48:49], v[34:35], v[48:49] op_sel_hi:[0,1]
	v_pk_mul_f32 v[84:85], v[34:35], v[84:85] op_sel_hi:[0,1]
	v_pk_mul_f32 v[50:51], v[34:35], v[50:51] op_sel_hi:[0,1]
	v_pk_mul_f32 v[36:37], v[34:35], v[36:37] op_sel_hi:[0,1]
	v_pk_mul_f32 v[98:99], v[34:35], v[46:47] op_sel_hi:[0,1]
	v_pk_mul_f32 v[100:101], v[58:59], v[106:107] op_sel_hi:[0,1]
	v_pk_mul_f32 v[64:65], v[58:59], v[64:65] op_sel_hi:[0,1]
	v_pk_mul_f32 v[102:103], v[58:59], v[122:123] op_sel_hi:[0,1]
	v_pk_mul_f32 v[66:67], v[58:59], v[66:67] op_sel_hi:[0,1]
	v_pk_mul_f32 v[104:105], v[58:59], v[110:111] op_sel_hi:[0,1]
	v_pk_mul_f32 v[70:71], v[58:59], v[70:71] op_sel_hi:[0,1]
	v_pk_mul_f32 v[106:107], v[58:59], v[60:61] op_sel_hi:[0,1]
	v_pk_mul_f32 v[108:109], v[58:59], v[62:63] op_sel_hi:[0,1]
	v_pk_fma_f32 v[30:31], v[8:9], v[30:31], v[28:29]
	v_pk_fma_f32 v[28:29], v[10:11], v[82:83], v[44:45]
	v_pk_fma_f32 v[34:35], v[12:13], v[48:49], v[72:73]
	v_pk_fma_f32 v[32:33], v[14:15], v[32:33], v[52:53]
	v_pk_fma_f32 v[46:47], v[16:17], v[50:51], v[76:77]
	v_pk_fma_f32 v[44:45], v[18:19], v[84:85], v[74:75]
	v_pk_fma_f32 v[50:51], v[20:21], v[98:99], v[80:81]
	v_pk_fma_f32 v[48:49], v[22:23], v[36:37], v[78:79]
	v_pk_fma_f32 v[54:55], v[8:9], v[64:65], v[54:55]
	v_pk_fma_f32 v[52:53], v[10:11], v[100:101], v[86:87]
	v_pk_fma_f32 v[58:59], v[12:13], v[66:67], v[56:57]
	v_pk_fma_f32 v[56:57], v[14:15], v[102:103], v[88:89]
	v_pk_fma_f32 v[62:63], v[16:17], v[70:71], v[92:93]
	v_pk_fma_f32 v[60:61], v[18:19], v[104:105], v[90:91]
	v_pk_fma_f32 v[66:67], v[20:21], v[108:109], v[96:97]
	v_pk_fma_f32 v[64:65], v[22:23], v[106:107], v[94:95]
	global_store_dwordx4 v[24:25], v[28:31], off offset:-3072 nt
	global_store_dwordx4 v[24:25], v[32:35], off offset:-2048 nt
	global_store_dwordx4 v[24:25], v[44:47], off offset:-1024 nt
	global_store_dwordx4 v[24:25], v[48:51], off nt
	global_store_dwordx4 v[68:69], v[52:55], off nt
	global_store_dwordx4 v[68:69], v[56:59], off offset:1024 nt
	global_store_dwordx4 v[68:69], v[60:63], off offset:2048 nt
	global_store_dwordx4 v[68:69], v[64:67], off offset:3072 nt
	v_lshl_add_u64 v[24:25], v[24:25], 0, s[6:7]
	s_cbranch_scc1 .LBB0_1714
